# Q K^T stage: Q and K row fragments read once in one batch (16 reads instead of 24 in three round trips), three tiles accumulate back to back, decay scaling after the last
# baseline (speedup 1.0000x reference)
; __device__ __forceinline__ void dn_task(const Params& p, int l, int task, char* smem) {
;     ...
;       const int did = tid >> 2, pp = did >> 2, wh = did & 3, part = tid & 3;
;       const float* xr = (wh == 0) ? (ks + (2 * pp + 1) * 68) : (wh == 1) ? (qs + (2 * pp) * 68) : (qs + (2 * pp + 1) * 68);
;       const float* yr = (wh == 3) ? (ks + (2 * pp + 1) * 68) : (ks + (2 * pp) * 68);
;       float sdot = 0.f;
; #pragma unroll
;       for (int i = 0; i < 16; ++i) sdot += xr[part * 16 + i] * yr[part * 16 + i];
;       sdot = quad_sum(sdot);
;       if (part == 0) dots[did] = sdot;
;     }
.Ldc_s2k:
	ds_read_b128 v[10:13], v224 offset:0
	ds_read_b128 v[14:17], v224 offset:16
	ds_read_b128 v[18:21], v224 offset:32
	ds_read_b128 v[22:25], v224 offset:48
	ds_read_b128 v[26:29], v224 offset:4352
	ds_read_b128 v[30:33], v224 offset:4368
	ds_read_b128 v[34:37], v224 offset:4384
	ds_read_b128 v[38:41], v224 offset:4400
	ds_read_b128 v[42:45], v224 offset:8704
	ds_read_b128 v[46:49], v224 offset:8720
	ds_read_b128 v[50:53], v224 offset:8736
	ds_read_b128 v[54:57], v224 offset:8752
	ds_read_b128 v[66:69], v224 offset:13056
	ds_read_b128 v[70:73], v224 offset:13072
	ds_read_b128 v[74:77], v224 offset:13088
	ds_read_b128 v[78:81], v224 offset:13104
	ds_read_b32 v82, v225 offset:53248
	ds_read_b32 v83, v225 offset:53392
	ds_read_b32 v84, v225 offset:53536
	ds_read_b32 v85, v225 offset:53680
	ds_read_b32 v86, v225 offset:55552
	ds_read_b32 v87, v225 offset:55696
	ds_read_b32 v88, v225 offset:55840
	ds_read_b32 v89, v225 offset:55984
	ds_read_b32 v226, v225 offset:55616
	ds_read_b32 v227, v225 offset:55760
	ds_read_b32 v228, v225 offset:55904
	ds_read_b32 v229, v225 offset:56048
	s_waitcnt lgkmcnt(0)
	v_mfma_f32_16x16x4_f32 v[58:61], v10, v42, 0
	v_mfma_f32_16x16x4_f32 v[58:61], v11, v43, v[58:61]
	v_mfma_f32_16x16x4_f32 v[58:61], v12, v44, v[58:61]
	v_mfma_f32_16x16x4_f32 v[58:61], v13, v45, v[58:61]
	v_mfma_f32_16x16x4_f32 v[58:61], v14, v46, v[58:61]
	v_mfma_f32_16x16x4_f32 v[58:61], v15, v47, v[58:61]
	v_mfma_f32_16x16x4_f32 v[58:61], v16, v48, v[58:61]
	v_mfma_f32_16x16x4_f32 v[58:61], v17, v49, v[58:61]
	v_mfma_f32_16x16x4_f32 v[58:61], v18, v50, v[58:61]
	v_mfma_f32_16x16x4_f32 v[58:61], v19, v51, v[58:61]
	v_mfma_f32_16x16x4_f32 v[58:61], v20, v52, v[58:61]
	v_mfma_f32_16x16x4_f32 v[58:61], v21, v53, v[58:61]
	v_mfma_f32_16x16x4_f32 v[58:61], v22, v54, v[58:61]
	v_mfma_f32_16x16x4_f32 v[58:61], v23, v55, v[58:61]
	v_mfma_f32_16x16x4_f32 v[58:61], v24, v56, v[58:61]
	v_mfma_f32_16x16x4_f32 v[58:61], v25, v57, v[58:61]
	v_mfma_f32_16x16x4_f32 v[62:65], v26, v42, 0
	v_mfma_f32_16x16x4_f32 v[62:65], v27, v43, v[62:65]
	v_mfma_f32_16x16x4_f32 v[62:65], v28, v44, v[62:65]
	v_mfma_f32_16x16x4_f32 v[62:65], v29, v45, v[62:65]
	v_mfma_f32_16x16x4_f32 v[62:65], v30, v46, v[62:65]
	v_mfma_f32_16x16x4_f32 v[62:65], v31, v47, v[62:65]
	v_mfma_f32_16x16x4_f32 v[62:65], v32, v48, v[62:65]
	v_mfma_f32_16x16x4_f32 v[62:65], v33, v49, v[62:65]
	v_mfma_f32_16x16x4_f32 v[62:65], v34, v50, v[62:65]
	v_mfma_f32_16x16x4_f32 v[62:65], v35, v51, v[62:65]
	v_mfma_f32_16x16x4_f32 v[62:65], v36, v52, v[62:65]
	v_mfma_f32_16x16x4_f32 v[62:65], v37, v53, v[62:65]
	v_mfma_f32_16x16x4_f32 v[62:65], v38, v54, v[62:65]
	v_mfma_f32_16x16x4_f32 v[62:65], v39, v55, v[62:65]
	v_mfma_f32_16x16x4_f32 v[62:65], v40, v56, v[62:65]
	v_mfma_f32_16x16x4_f32 v[62:65], v41, v57, v[62:65]
	v_mfma_f32_16x16x4_f32 v[230:233], v26, v66, 0
	v_mfma_f32_16x16x4_f32 v[230:233], v27, v67, v[230:233]
	v_mfma_f32_16x16x4_f32 v[230:233], v28, v68, v[230:233]
	v_mfma_f32_16x16x4_f32 v[230:233], v29, v69, v[230:233]
	v_mfma_f32_16x16x4_f32 v[230:233], v30, v70, v[230:233]
	v_mfma_f32_16x16x4_f32 v[230:233], v31, v71, v[230:233]
	v_mfma_f32_16x16x4_f32 v[230:233], v32, v72, v[230:233]
	v_mfma_f32_16x16x4_f32 v[230:233], v33, v73, v[230:233]
	v_mfma_f32_16x16x4_f32 v[230:233], v34, v74, v[230:233]
	v_mfma_f32_16x16x4_f32 v[230:233], v35, v75, v[230:233]
	v_mfma_f32_16x16x4_f32 v[230:233], v36, v76, v[230:233]
	v_mfma_f32_16x16x4_f32 v[230:233], v37, v77, v[230:233]
	v_mfma_f32_16x16x4_f32 v[230:233], v38, v78, v[230:233]
	v_mfma_f32_16x16x4_f32 v[230:233], v39, v79, v[230:233]
	v_mfma_f32_16x16x4_f32 v[230:233], v40, v80, v[230:233]
	v_mfma_f32_16x16x4_f32 v[230:233], v41, v81, v[230:233]
	s_nop 7
	s_nop 3
	v_mul_f32_e32 v58, v58, v82
	ds_write_b32 v225, v58 offset:48640
	v_mul_f32_e32 v59, v59, v83
	ds_write_b32 v225, v59 offset:48784
	v_mul_f32_e32 v60, v60, v84
	ds_write_b32 v225, v60 offset:48928
	v_mul_f32_e32 v61, v61, v85
	ds_write_b32 v225, v61 offset:49072
	v_mul_f32_e32 v62, v62, v86
	ds_write_b32 v225, v62 offset:50944
	v_mul_f32_e32 v63, v63, v87
	ds_write_b32 v225, v63 offset:51088
	v_mul_f32_e32 v64, v64, v88
	ds_write_b32 v225, v64 offset:51232
	v_mul_f32_e32 v65, v65, v89
	ds_write_b32 v225, v65 offset:51376
	v_mul_f32_e32 v230, v230, v226
	ds_write_b32 v225, v230 offset:51008
	v_mul_f32_e32 v231, v231, v227
	ds_write_b32 v225, v231 offset:51152
	v_mul_f32_e32 v232, v232, v228
	ds_write_b32 v225, v232 offset:51296
	v_mul_f32_e32 v233, v233, v229
	ds_write_b32 v225, v233 offset:51440
	s_branch .Ldc_b3
